# v12 + attention loop exact vmcnt: latch waits only for Q loads (vmcnt 7/6), no drain of previous item's O/LSE stores at loop top
# baseline (speedup 1.0000x reference)
; __device__ __forceinline__ int ltid(int wave) { int t = (wave << 6) | (int)__builtin_amdgcn_mbcnt_hi(~0u, __builtin_amdgcn_mbcnt_lo(~0u, 0u)); asm volatile("" : "+v"(t)); return t; }
; __device__ __forceinline__ int lbid() { int b = blockIdx.x; asm volatile("" : "+s"(b)); return b; }
; __device__ void attn_items(const Params& p, unsigned char* shm) {
;     ...
;     const int tid = ltid(p.wave), lane = tid & 63, w = tid >> 6, fr = lane & 15, fq = lane >> 4, G_ = gridDim.x;
;     for (int i = tid; i < 24 * 129; i += 512) { const int hd = i / 129, j = i % 129; BT[hd * 132 + j] = p.in[21][(int)BUCKET[hd >> 3][j] * 24 + hd]; }
;     u32x4 kreg[5], vreg[5]; bf16x8 q0r, q1r;
;     const int total = 24 * 192;
;     int it = lbid();
;     ...
;             m = fmaxf(m, __shfl_xor(m, 1)); m = fmaxf(m, __shfl_xor(m, 2)); m = fmaxf(m, __shfl_xor(m, 4)); m = fmaxf(m, __shfl_xor(m, 8));
;             float sum = 0.f;
; #pragma unroll
;             for (int kt = 0; kt < 9; ++kt) { const float pv = __expf(s[kt][i] - m); s[kt][i] = pv; sum += pv; }
;             sum += __shfl_xor(sum, 1); sum += __shfl_xor(sum, 2); sum += __shfl_xor(sum, 4); sum += __shfl_xor(sum, 8);
.LBB0_338:
	v_and_b32_e32 v2, 63, v130
	s_movk_i32 s22, 0xc00
	s_andn2_b64 vcc, exec, s[40:41]
	s_cbranch_vccnz .LBB0_453
	v_and_b32_e32 v0, 48, v130
	v_and_b32_e32 v50, 64, v140
	v_add_u32_e32 v101, 0, v0
	v_xor_b32_e32 v0, 1, v140
	v_add_u32_e32 v50, 64, v50
	v_cmp_lt_i32_e32 vcc, v0, v50
	s_movk_i32 s0, 0x1500
	v_lshlrev_b32_e32 v99, 4, v47
	v_cndmask_b32_e32 v0, v140, v0, vcc
	v_lshlrev_b32_e32 v103, 2, v0
	v_xor_b32_e32 v0, 2, v140
	v_cmp_lt_i32_e32 vcc, v0, v50
	v_and_b32_e32 v92, 56, v48
	v_lshlrev_b32_e32 v51, 4, v46
	v_cndmask_b32_e32 v0, v140, v0, vcc
	v_lshlrev_b32_e32 v104, 2, v0
	v_xor_b32_e32 v0, 4, v140
	v_cmp_lt_i32_e32 vcc, v0, v50
	s_mov_b64 s[86:87], s[90:91]
	v_add_u32_e32 v61, 0x200, v130
	v_cndmask_b32_e32 v0, v140, v0, vcc
	v_lshlrev_b32_e32 v105, 2, v0
	v_xor_b32_e32 v0, 8, v140
	v_cmp_lt_i32_e32 vcc, v0, v50
	v_ashrrev_i32_e32 v110, 3, v61
	s_movk_i32 s1, 0x680
	v_cndmask_b32_e32 v0, v140, v0, vcc
	v_lshlrev_b32_e32 v106, 2, v0
	v_mul_lo_u32 v0, v47, s0
	v_readlane_b32 s0, v254, 9
	v_cmp_gt_i32_e64 s[42:43], s1, v130
	v_add_u32_e32 v63, 0x400, v130
	v_add_u32_e32 v47, s0, v0
	s_movk_i32 s0, 0x880
	v_cmp_gt_i32_e64 s[6:7], s0, v130
	s_movk_i32 s0, 0x100
	v_mul_u32_u24_e32 v0, 0x150, v93
	v_cmp_gt_i32_e64 s[8:9], s0, v98
	v_add3_u32 v107, v47, v0, v51
	v_lshlrev_b32_e32 v0, 1, v92
	v_writelane_b32 v255, s8, 10
	v_lshl_add_u64 v[94:95], s[90:91], 0, v[0:1]
	s_mov_b64 s[90:91], s[6:7]
	v_writelane_b32 v255, s9, 11
	s_and_b64 s[6:7], s[6:7], s[8:9]
	v_writelane_b32 v255, s6, 14
	v_cmp_gt_i32_e64 s[18:19], s0, v110
	v_ashrrev_i32_e32 v111, 3, v63
	v_writelane_b32 v255, s7, 15
	v_writelane_b32 v255, s18, 16
	s_and_b64 s[6:7], s[42:43], s[18:19]
	s_movk_i32 s1, 0x480
	v_writelane_b32 v255, s19, 17
	v_writelane_b32 v255, s6, 18
	v_cmp_gt_i32_e64 s[38:39], s0, v111
	v_cmp_gt_i32_e64 s[46:47], s1, v130
	v_writelane_b32 v255, s7, 19
	v_writelane_b32 v255, s38, 20
	v_add_u32_e32 v65, 0x600, v130
	s_and_b64 s[6:7], s[46:47], s[38:39]
	v_writelane_b32 v255, s39, 21
	v_ashrrev_i32_e32 v112, 3, v65
	v_writelane_b32 v255, s6, 22
	s_movk_i32 s3, 0x280
	v_cmp_gt_i32_e64 s[40:41], s0, v112
	v_writelane_b32 v255, s7, 23
	v_cmp_gt_i32_e64 s[50:51], s3, v130
	v_writelane_b32 v255, s40, 24
	v_add_u32_e32 v67, 0x800, v130
	s_and_b64 s[6:7], s[50:51], s[40:41]
	v_writelane_b32 v255, s41, 25
	v_ashrrev_i32_e32 v113, 3, v67
	s_movk_i32 s1, 0x80
	v_writelane_b32 v255, s6, 26
	v_cmp_gt_i32_e64 s[54:55], s1, v130
	v_cmp_gt_i32_e64 s[0:1], s0, v113
	v_writelane_b32 v255, s7, 27
	v_lshlrev_b32_e32 v48, 2, v46
	v_writelane_b32 v255, s0, 28
	v_sub_u32_e32 v115, v93, v48
	v_add_u32_e32 v76, 0x80, v115
	v_writelane_b32 v255, s1, 29
	s_and_b64 s[0:1], s[54:55], s[0:1]
	v_writelane_b32 v255, s0, 30
	v_or_b32_e32 v77, 2, v48
	v_sub_u32_e32 v118, v93, v77
	v_writelane_b32 v255, s1, 31
	s_movk_i32 s0, 0x81
	v_cmp_gt_u32_e64 s[6:7], s0, v115
	v_add_u32_e32 v119, 0x80, v118
	v_or_b32_e32 v108, v48, v99
	v_writelane_b32 v254, s6, 49
	v_lshl_add_u32 v50, v93, 1, v47
	v_lshlrev_b32_e32 v44, 3, v46
	v_writelane_b32 v254, s7, 50
	v_cmp_gt_u32_e64 s[6:7], s0, v76
	v_or_b32_e32 v76, 1, v48
	v_sub_u32_e32 v116, v93, v76
	v_writelane_b32 v254, s6, 37
	v_add_u32_e32 v117, 0x80, v116
	v_or_b32_e32 v48, 3, v48
	v_writelane_b32 v254, s7, 38
	v_cmp_gt_u32_e64 s[6:7], s0, v116
	v_sub_u32_e32 v120, v93, v48
	v_add_u32_e32 v121, 0x80, v120
	v_writelane_b32 v255, s6, 0
	v_add_u32_e32 v51, v44, v99
	v_mul_u32_u24_e32 v48, 0x540, v46
	v_writelane_b32 v255, s7, 1
	v_cmp_gt_u32_e64 s[6:7], s0, v117
	v_or_b32_e32 v127, 16, v93
	v_bitop3_b32 v78, v51, v127, 24 bitop3:0x78
	v_writelane_b32 v255, s6, 2
	v_or_b32_e32 v129, 32, v93
	v_bitop3_b32 v79, v51, v129, 40 bitop3:0x78
	v_writelane_b32 v255, s7, 3
	v_cmp_gt_u32_e64 s[6:7], s0, v118
	v_or_b32_e32 v132, 48, v93
	v_bitop3_b32 v80, v51, v132, 56 bitop3:0x78
	v_writelane_b32 v255, s6, 4
	v_and_b32_e32 v3, 7, v130
	v_lshlrev_b32_e32 v49, 3, v3
	v_writelane_b32 v255, s7, 5
	v_cmp_gt_u32_e64 s[6:7], s0, v119
	v_or_b32_e32 v100, v99, v93
	v_lshrrev_b32_e32 v109, 3, v2
	v_writelane_b32 v255, s6, 6
	s_movk_i32 s2, 0x90
	v_xor_b32_e32 v60, v49, v98
	v_writelane_b32 v255, s7, 7
	v_cmp_gt_u32_e64 s[6:7], s0, v120
	v_cmp_gt_u32_e64 s[0:1], s0, v121
	v_xor_b32_e32 v62, v110, v49
	v_writelane_b32 v255, s6, 12
	v_xor_b32_e32 v64, v111, v49
	v_xor_b32_e32 v66, v112, v49
	v_writelane_b32 v255, s7, 13
	v_writelane_b32 v255, s0, 8
	v_xor_b32_e32 v49, v113, v49
	v_mul_lo_u32 v114, v100, s2
	v_writelane_b32 v255, s1, 9
	s_movk_i32 s0, 0x540
	v_mad_u32_u24 v122, v46, s0, v50
	s_movk_i32 s0, 0x150
	v_mad_u32_u24 v77, v76, s0, s0
; __device__ __forceinline__ bf16_t f2bf(float f) { return (bf16_t)(cvt_pk_bf16(f, 0.f) & 0xffffu); }
; __device__ void attn_items(const Params& p, unsigned char* shm) {
;     ...
;         bf16_t* Pw = Ps + w * 16 * 168;
; #pragma unroll
;         for (int i = 0; i < 4; ++i) {
; #pragma unroll
;             for (int kt = 0; kt < 9; ++kt) Pw[(fq * 4 + i) * 168 + 16 * kt + fr] = f2bf(s[kt][i]);
;             Pw[(fq * 4 + i) * 168 + 144 + fr] = 0; }
;         __syncthreads();
;         f32x4 o[4];
; #pragma unroll
;         for (int nt = 0; nt < 4; ++nt) o[nt] = (f32x4){0.f, 0.f, 0.f, 0.f};
; #pragma unroll
;         for (int ks = 0; ks < 5; ++ks) { const bf16x8 ap = *(const bf16x8*)(Pw + fr * 168 + ks * 32 + fq * 8);
; #pragma unroll
;             for (int nt = 0; nt < 4; ++nt) { const int dim = nt * 16 + fr; o[nt] = __builtin_amdgcn_mfma_f32_16x16x32_bf16(ap, *(const bf16x8*)(Vt + dim * 320 + ((16 * w + ks * 32 + fq * 8) ^ ((dim >> 3) << 3))), o[nt], 0, 0, 0); } }
;     ...
; #pragma unroll
;         for (int h = 0; h < 2; ++h) { const int c = lane + 64 * h, row = c >> 3, c8 = c & 7;
;             *(u32x4*)(Qb + (size_t)(G.seq_start + G.r + G.dil * (G.q0 + 16 * w + row)) * 1536 + G.hd * 64 + c8 * 8) = *(const u32x4*)(Pw + row * 168 + c8 * 8); }
;         __syncthreads();
	v_add_u32_e32 v124, v50, v77
	v_mov_b32_e32 v77, 0x2a0
	v_mul_u32_u24_e32 v46, 0x150, v76
	v_mad_u32_u24 v123, v76, s0, v50
	v_mad_u32_u24 v76, v76, s0, v77
	v_add_u32_e32 v125, v50, v76
	v_mad_u32_u24 v76, v93, s3, 0
	v_bitop3_b32 v77, v51, v130, 8 bitop3:0x78
	v_lshl_add_u32 v126, v77, 1, v76
	v_add_u32_e32 v77, 0x2800, v76
	v_lshl_add_u32 v128, v78, 1, v77
	v_add_u32_e32 v78, 0x5000, v76
	v_lshl_add_u32 v131, v79, 1, v78
	v_add_u32_e32 v79, 0x7800, v76
	v_lshl_add_u32 v133, v80, 1, v79
	v_add_u32_e32 v80, 32, v51
	v_bitop3_b32 v81, v80, v130, 8 bitop3:0x78
	v_lshl_add_u32 v134, v81, 1, v76
	v_bitop3_b32 v81, v80, v127, 24 bitop3:0x78
	v_lshl_add_u32 v135, v81, 1, v77
	v_bitop3_b32 v81, v80, v129, 40 bitop3:0x78
	v_bitop3_b32 v80, v80, v132, 56 bitop3:0x78
	v_lshl_add_u32 v137, v80, 1, v79
	v_add_u32_e32 v80, 64, v51
	v_lshl_add_u32 v136, v81, 1, v78
	v_bitop3_b32 v81, v80, v130, 8 bitop3:0x78
	v_lshl_add_u32 v138, v81, 1, v76
	v_bitop3_b32 v81, v80, v127, 24 bitop3:0x78
	v_lshl_add_u32 v139, v81, 1, v77
	v_bitop3_b32 v81, v80, v129, 40 bitop3:0x78
	v_bitop3_b32 v80, v80, v132, 56 bitop3:0x78
	v_lshl_add_u32 v141, v80, 1, v79
	v_add_u32_e32 v80, 0x60, v51
	v_lshl_add_u32 v140, v81, 1, v78
	v_bitop3_b32 v81, v80, v130, 8 bitop3:0x78
	v_lshl_add_u32 v142, v81, 1, v76
	v_bitop3_b32 v81, v80, v127, 24 bitop3:0x78
	v_lshl_add_u32 v143, v81, 1, v77
	v_bitop3_b32 v81, v80, v129, 40 bitop3:0x78
	v_bitop3_b32 v80, v80, v132, 56 bitop3:0x78
	v_add_u32_e32 v51, 0x80, v51
	v_lshl_add_u32 v145, v80, 1, v79
	v_bitop3_b32 v80, v51, v130, 8 bitop3:0x78
	v_lshl_add_u32 v130, v80, 1, v76
	v_bitop3_b32 v76, v51, v127, 24 bitop3:0x78
	v_lshl_add_u32 v146, v76, 1, v77
	v_bitop3_b32 v76, v51, v129, 40 bitop3:0x78
	v_bitop3_b32 v51, v51, v132, 56 bitop3:0x78
	v_or_b32_e32 v149, 8, v109
	v_lshl_add_u32 v45, v3, 4, 0
	v_add_u32_e32 v47, v47, v0
	v_mul_u32_u24_e32 v0, 0x150, v109
	v_mul_lo_u32 v2, v98, s2
	v_lshl_add_u32 v60, v60, 1, 0
	v_mul_u32_u24_e32 v3, 0x1400, v3
	v_mul_lo_u32 v61, v110, s2
	v_lshl_add_u32 v62, v62, 1, 0
	v_mul_lo_u32 v63, v111, s2
	v_lshl_add_u32 v64, v64, 1, 0
	v_mul_lo_u32 v65, v112, s2
	v_lshl_add_u32 v66, v66, 1, 0
	v_mul_lo_u32 v67, v113, s2
	v_lshl_add_u32 v49, v49, 1, 0
	v_add_u32_e32 v68, 0x900, v114
	v_add_u32_e32 v69, 0x1200, v114
	v_add_u32_e32 v70, 0x1b00, v114
	v_add_u32_e32 v71, 0x2400, v114
	v_add_u32_e32 v72, 0x2d00, v114
	v_add_u32_e32 v73, 0x3600, v114
	v_add_u32_e32 v74, 0x3f00, v114
	v_add_u32_e32 v75, 0x4800, v114
	v_lshl_add_u32 v148, v51, 1, v79
	v_mul_u32_u24_e32 v51, 0x150, v149
	v_readlane_b32 s0, v251, 10
	s_movk_i32 s23, 0xff7f
	v_subrev_u32_e32 v102, 64, v99
	v_cmp_eq_u32_e64 s[36:37], 0, v93
	v_lshl_add_u32 v144, v81, 1, v78
	v_lshl_add_u32 v147, v76, 1, v78
	v_or_b32_e32 v150, 0x50, v93
	v_or_b32_e32 v151, 0x60, v93
	v_or_b32_e32 v152, 0x70, v93
	v_or_b32_e32 v153, 0x80, v93
	s_lshl_b32 s2, s4, 7
	s_lshl_b32 s3, s0, 7
	v_add_u32_e32 v154, v45, v2
	v_add_u32_e32 v155, v60, v3
	v_add_u32_e32 v156, v45, v61
	v_add_u32_e32 v157, v62, v3
	v_add_u32_e32 v158, v45, v63
	v_add_u32_e32 v159, v64, v3
	v_add_u32_e32 v160, v45, v65
	v_add_u32_e32 v161, v66, v3
	v_add_u32_e32 v162, v45, v67
	v_add_u32_e32 v163, v49, v3
	v_lshlrev_b32_e32 v96, 1, v44
	v_add_u32_e32 v164, v101, v68
	v_add_u32_e32 v165, v101, v69
	v_add_u32_e32 v166, v101, v70
	v_add_u32_e32 v167, v101, v71
	v_add_u32_e32 v168, v101, v72
	v_add_u32_e32 v169, v101, v73
	v_add_u32_e32 v170, v101, v74
	v_add_u32_e32 v171, v101, v75
	v_add_u32_e32 v172, v50, v48
	v_add_u32_e32 v173, v47, v0
	v_add_u32_e32 v174, v47, v51
	v_add_u32_e32 v175, v50, v46
	v_readlane_b32 s1, v251, 11
	s_waitcnt vmcnt(0)
	s_branch .LBB0_341
.LBB0_340:
	s_or_b64 exec, exec, s[0:1]
	s_waitcnt lgkmcnt(0)
	s_barrier
	ds_read_b128 v[52:55], v173
	s_lshl_b32 s0, s58, 6
	v_or_b32_e32 v56, v0, v109
	s_ashr_i32 s1, s0, 31
	v_lshlrev_b32_e32 v56, s4, v56
	v_lshl_add_u64 v[2:3], s[0:1], 1, v[94:95]
	v_add_u32_e32 v56, s6, v56
	s_movk_i32 s5, 0xc00
	v_mad_i64_i32 v[56:57], s[0:1], v56, s5, v[2:3]
	s_waitcnt lgkmcnt(0)
	global_store_dwordx4 v[56:57], v[52:55], off
	ds_read_b128 v[52:55], v174
	v_or_b32_e32 v0, v0, v149
	v_lshlrev_b32_e32 v0, s4, v0
	v_add_u32_e32 v0, s6, v0
	v_mad_i64_i32 v[2:3], s[0:1], v0, s5, v[2:3]
	s_waitcnt lgkmcnt(0)
	global_store_dwordx4 v[2:3], v[52:55], off
	s_waitcnt vmcnt(7)
	v_mov_b64_e32 v[58:59], v[46:47]
	s_movk_i32 s22, 0xc00
	s_waitcnt vmcnt(6)
	v_mov_b64_e32 v[54:55], v[50:51]
	s_add_i32 s2, s2, s3
	s_and_b64 vcc, exec, s[40:41]
	v_mov_b64_e32 v[56:57], v[44:45]
	v_mov_b64_e32 v[52:53], v[48:49]
	s_mov_b32 s4, s15
	s_barrier
	s_cbranch_vccnz .LBB0_793

; __device__ void attn_items(const Params& p, unsigned char* shm) {
;     ...
;     for (; it < total; it += G_) {
;         const AttnGeom G = attn_geom(it);
; #pragma unroll
;         for (int i = 0; i < 5; ++i) { const int e = tid + 512 * i, kk = e >> 3, c8 = e & 7;
;             if (e < 2176) {
;                 if (kk < 256) *(u32x4*)(Ks + kk * 72 + c8 * 8) = kreg[i];
; #pragma unroll
;                 for (int j = 0; j < 8; ++j) Vt[(c8 * 8 + j) * 320 + (kk ^ (c8 << 3))] = (bf16_t)((vreg[i][j >> 1] >> ((j & 1) * 16)) & 0xffffu); } }
;         const bf16x8 aq0 = q0r, aq1 = q1r;
;         __syncthreads();
;         if (it + G_ < total) ATT_LOAD(it + G_);
.LBB0_346:
	s_mov_b64 s[38:39], exec
	v_readlane_b32 s6, v255, 10
	v_readlane_b32 s7, v255, 11
	s_and_b64 s[6:7], s[38:39], s[6:7]
	s_mov_b64 exec, s[6:7]
	s_cbranch_execz .LBB0_348
	ds_write_b128 v154, v[8:11]
.LBB0_348:
	s_or_b64 exec, exec, s[38:39]
	ds_write_b16 v155, v12 offset:36864
	ds_write_b16_d16_hi v155, v12 offset:37504
	ds_write_b16 v155, v13 offset:38144
	ds_write_b16_d16_hi v155, v13 offset:38784
	ds_write_b16 v155, v14 offset:39424
	ds_write_b16_d16_hi v155, v14 offset:40064
	ds_write_b16 v155, v15 offset:40704
	ds_write_b16_d16_hi v155, v15 offset:41344
	s_or_b64 exec, exec, s[0:1]
	s_and_saveexec_b64 s[0:1], s[42:43]
	s_cbranch_execz .LBB0_343
.LBB0_349:
	s_mov_b64 s[38:39], exec
	v_readlane_b32 s6, v255, 16
	v_readlane_b32 s7, v255, 17
	s_and_b64 s[6:7], s[38:39], s[6:7]
	s_mov_b64 exec, s[6:7]
	s_cbranch_execz .LBB0_351
	ds_write_b128 v156, v[16:19]
.LBB0_351:
	s_or_b64 exec, exec, s[38:39]
	ds_write_b16 v157, v4 offset:36864
	ds_write_b16_d16_hi v157, v4 offset:37504
	ds_write_b16 v157, v5 offset:38144
	ds_write_b16_d16_hi v157, v5 offset:38784
	ds_write_b16 v157, v6 offset:39424
	ds_write_b16_d16_hi v157, v6 offset:40064
	ds_write_b16 v157, v7 offset:40704
	ds_write_b16_d16_hi v157, v7 offset:41344
	s_or_b64 exec, exec, s[0:1]
	s_and_saveexec_b64 s[0:1], s[46:47]
	s_cbranch_execz .LBB0_344
.LBB0_352:
	s_mov_b64 s[38:39], exec
	v_readlane_b32 s6, v255, 20
	v_readlane_b32 s7, v255, 21
	s_and_b64 s[6:7], s[38:39], s[6:7]
	s_mov_b64 exec, s[6:7]
	s_cbranch_execz .LBB0_354
	ds_write_b128 v158, v[20:23]
.LBB0_354:
	s_or_b64 exec, exec, s[38:39]
	ds_write_b16 v159, v24 offset:36864
	ds_write_b16_d16_hi v159, v24 offset:37504
	ds_write_b16 v159, v25 offset:38144
	ds_write_b16_d16_hi v159, v25 offset:38784
	ds_write_b16 v159, v26 offset:39424
	ds_write_b16_d16_hi v159, v26 offset:40064
	ds_write_b16 v159, v27 offset:40704
	ds_write_b16_d16_hi v159, v27 offset:41344
	s_or_b64 exec, exec, s[0:1]
	s_and_saveexec_b64 s[0:1], s[50:51]
	s_cbranch_execz .LBB0_345
.LBB0_355:
	s_mov_b64 s[38:39], exec
	v_readlane_b32 s6, v255, 24
	v_readlane_b32 s7, v255, 25
	s_and_b64 s[6:7], s[38:39], s[6:7]
	s_mov_b64 exec, s[6:7]
	s_cbranch_execz .LBB0_357
	ds_write_b128 v160, v[28:31]
.LBB0_357:
	s_or_b64 exec, exec, s[38:39]
	ds_write_b16 v161, v32 offset:36864
	ds_write_b16_d16_hi v161, v32 offset:37504
	ds_write_b16 v161, v33 offset:38144
	ds_write_b16_d16_hi v161, v33 offset:38784
	ds_write_b16 v161, v34 offset:39424
	ds_write_b16_d16_hi v161, v34 offset:40064
	ds_write_b16 v161, v35 offset:40704
	ds_write_b16_d16_hi v161, v35 offset:41344
	s_or_b64 exec, exec, s[0:1]
	s_and_saveexec_b64 s[0:1], s[54:55]
	s_cbranch_execz .LBB0_361
.LBB0_358:
	s_mov_b64 s[38:39], exec
	v_readlane_b32 s6, v255, 28
	v_readlane_b32 s7, v255, 29
	s_and_b64 s[6:7], s[38:39], s[6:7]
	s_mov_b64 exec, s[6:7]
	s_cbranch_execz .LBB0_360
	ds_write_b128 v162, v[40:43]
.LBB0_360:
	s_or_b64 exec, exec, s[38:39]
	ds_write_b16 v163, v36 offset:36864
	ds_write_b16_d16_hi v163, v36 offset:37504
	ds_write_b16 v163, v37 offset:38144
	ds_write_b16_d16_hi v163, v37 offset:38784
	ds_write_b16 v163, v38 offset:39424
	ds_write_b16_d16_hi v163, v38 offset:40064
	ds_write_b16 v163, v39 offset:40704
	ds_write_b16_d16_hi v163, v39 offset:41344
.LBB0_361:
	s_or_b64 exec, exec, s[0:1]
	v_readlane_b32 s0, v251, 10
	s_add_i32 s15, s4, s0
	s_cmpk_gt_i32 s15, 0x11ff
	s_cselect_b64 s[40:41], -1, 0
	v_mov_b64_e32 v[44:45], v[56:57]
	v_mov_b64_e32 v[48:49], v[52:53]
	s_and_b64 vcc, exec, s[40:41]
	v_mov_b64_e32 v[46:47], v[58:59]
	v_mov_b64_e32 v[50:51], v[54:55]
	s_waitcnt lgkmcnt(0)
	s_barrier
	v_readlane_b32 s1, v251, 11
	s_cbranch_vccnz .LBB0_373
	s_mul_hi_i32 s0, s15, 0x2aaaaaab
	s_lshr_b32 s1, s0, 31
	s_ashr_i32 s0, s0, 5
	s_add_i32 s0, s0, s1
	s_mul_i32 s1, s0, 0xffffff40
	s_mul_i32 s5, s0, 0xffffa000
	s_add_i32 s6, s3, s2
	s_add_i32 s1, s15, s1
	s_add_i32 s6, s6, s5
	s_and_b32 s6, s6, 0xfffff800
	s_and_b32 s7, s1, 15
	s_sub_i32 s8, s1, 64
	s_and_b32 s5, s0, -8
	s_cmp_eq_u32 s5, 8
	s_cselect_b32 s5, 2, 4
	s_cmp_gt_u32 s0, 7
	s_cselect_b32 s5, s5, 0
	s_cmp_lt_i32 s1, 64
	s_cselect_b32 s1, s7, s8
	s_movk_i32 s7, 0x800
	s_cselect_b32 s7, s7, 0x4000
	s_cselect_b32 s10, s6, 0x2000
	s_cselect_b32 s6, 4, 7
	s_lshr_b32 s8, s7, s5
	s_lshr_b32 s7, s8, 7
	s_sub_i32 s6, s6, s5
	s_add_i32 s7, s7, -1
	s_lshr_b32 s17, s1, s6
	s_and_b32 s1, s7, s1
	s_lshl_b32 s6, s1, 7
	s_sub_i32 s9, s6, 64
	s_lshl_b32 s38, s0, 6
	v_add_u32_e32 v16, s9, v98
	v_readlane_b32 s0, v255, 14
	v_cmp_lt_i32_e32 vcc, -1, v16
	v_readlane_b32 s1, v255, 15
	v_mov_b32_e32 v2, v1
	v_mov_b32_e32 v3, v1
	v_mov_b32_e32 v6, v1
	v_mov_b32_e32 v7, v1
	s_ashr_i32 s39, s38, 31
	s_and_b64 s[0:1], s[0:1], vcc
	v_cmp_gt_i32_e32 vcc, s8, v16
	v_mov_b32_e32 v0, v1
	v_mov_b32_e32 v4, v1
	v_mov_b32_e32 v5, v1
	v_mov_b64_e32 v[14:15], v[6:7]
	v_mov_b64_e32 v[10:11], v[2:3]
	s_add_i32 s7, s17, s10
	v_mov_b32_e32 v45, s39
	v_or_b32_e32 v44, s38, v92
	s_and_b64 s[18:19], s[0:1], vcc
	v_mov_b64_e32 v[12:13], v[4:5]
	v_mov_b64_e32 v[8:9], v[0:1]
	s_and_saveexec_b64 s[0:1], s[18:19]
	s_cbranch_execz .LBB0_364
	v_lshlrev_b32_e32 v0, s5, v16
	v_add_u32_e32 v0, s7, v0
	v_mad_i64_i32 v[2:3], s[18:19], v0, s95, v[44:45]
	v_readlane_b32 s18, v252, 23
	v_lshlrev_b64 v[2:3], 1, v[2:3]
	v_readlane_b32 s19, v252, 24
	s_nop 1
	v_lshl_add_u64 v[8:9], s[18:19], 0, v[2:3]
	v_readlane_b32 s18, v252, 25
	v_readlane_b32 s19, v252, 26
	s_nop 1
	v_lshl_add_u64 v[2:3], s[18:19], 0, v[2:3]
	global_load_dwordx4 v[8:11], v[8:9], off
	s_nop 0
	global_load_dwordx4 v[12:15], v[2:3], off
